# phase_lru_scan: hand-written fast path for gridDim=256 (ax/g/y moved with 16-byte global accesses through LDS tiles instead of per-element 2/4-byte accesses; compiler code kept as fallback for other g
# speedup vs baseline: 1.0013x; 1.0013x over previous
; #define LAS __attribute__((address_space(3)))
; DI int otid() { int t = threadIdx.x; asm volatile("" : "+v"(t)); return t; }
; DI void phase_lru_scan(const Params& p, LAS unsigned char* lds) {
;     const unsigned* ax = (const unsigned*)(p.ws + ACT + 128 * MiB); const bf16_t* big = (const bf16_t*)(p.ws + ACT);
;     bf16_t* y = (bf16_t*)(p.ws + HBUF);
;     LAS unsigned* tile = (LAS unsigned*)lds;
;     LAS float* sP = (LAS float*)(lds + 65536); LAS float* sH = sP + 512; LAS float* sC = sH + 512;
;     const int tid = otid(), seg = tid >> 5, chl = tid & 31;
;     for (int u = blockIdx.x; u < 256; u += gridDim.x) {
;         const int b = u >> 6, ch = (u & 63) * 32 + chl;
;         const size_t rowbase = (size_t)b * SEQ;
;         unsigned pre[32];
; #pragma unroll
;         for (int i = 0; i < 32; ++i) pre[i] = ax[(rowbase + seg + 16 * i) * DM + ch];
;         __syncthreads();
;         if (tid < 32) sC[tid] = 0.f;
;         for (int sc = 0; sc < 8; ++sc) {
; #pragma unroll
;             for (int i = 0; i < 32; ++i) tile[(seg + 16 * i) * 32 + chl] = pre[i];
;             __syncthreads();
;             if (sc + 1 < 8) {
; #pragma unroll
;                 for (int i = 0; i < 32; ++i) pre[i] = ax[(rowbase + (sc + 1) * 512 + seg + 16 * i) * DM + ch];
;             }
;             const size_t r0 = rowbase + sc * 512 + seg * 32;
.LBB0_1009:
	s_or_b64 exec, exec, s[8:9]
	v_mov_b32_e32 v4, v181
	s_and_b64 vcc, exec, s[6:7]
	s_waitcnt lgkmcnt(0)
	s_barrier
	s_cbranch_vccnz .LBB0_1026
	s_cmp_eq_u32 s18, 0x100
	s_cbranch_scc0 .Llr_orig
	s_load_dwordx2 s[6:7], s[0:1], 0xf0
	v_and_b32_e32 v126, 31, v181
	v_lshrrev_b32_e32 v113, 5, v181
	v_lshlrev_b32_e32 v112, 2, v126
	v_lshl_add_u32 v114, v113, 12, v112
	v_lshlrev_b32_e32 v127, 1, v126
	v_lshl_add_u32 v115, v113, 11, v127
	v_add_u32_e32 v115, 65536, v115
	v_lshlrev_b32_e32 v116, 2, v181
	v_add_u32_e32 v116, 98304, v116
	v_add_u32_e32 v117, 98304, v112
	v_lshrrev_b32_e32 v128, 3, v181
	v_and_b32_e32 v129, 7, v181
	v_lshlrev_b32_e32 v118, 7, v128
	v_lshl_add_u32 v118, v129, 4, v118
	v_lshlrev_b32_e32 v120, 13, v128
	v_lshl_add_u32 v120, v129, 4, v120
	v_lshrrev_b32_e32 v128, 2, v181
	v_and_b32_e32 v129, 3, v181
	v_lshlrev_b32_e32 v119, 6, v128
	v_lshl_add_u32 v119, v129, 4, v119
	v_add_u32_e32 v119, 65536, v119
	v_lshlrev_b32_e32 v121, 13, v128
	v_lshl_add_u32 v121, v129, 4, v121
	v_lshlrev_b32_e32 v122, 12, v128
	v_lshl_add_u32 v122, v129, 4, v122
	s_lshr_b32 s8, s2, 6
	s_and_b32 s9, s2, 63
	s_lshl_b32 s10, s8, 25
	s_lshl_b32 s11, s9, 7
	s_waitcnt lgkmcnt(0)
	s_add_u32 s12, s6, 0x13f00000
	s_addc_u32 s13, s7, 0
	s_add_u32 s12, s12, s10
	s_addc_u32 s13, s13, 0
	s_add_u32 s12, s12, s11
	s_addc_u32 s13, s13, 0
	s_lshl_b32 s11, s9, 6
	s_add_u32 s14, s6, 0xbf01000
	s_addc_u32 s15, s7, 0
	s_add_u32 s14, s14, s10
	s_addc_u32 s15, s15, 0
	s_add_u32 s14, s14, s11
	s_addc_u32 s15, s15, 0
	s_lshl_b32 s10, s8, 24
	s_add_u32 s16, s6, 0x7f00000
	s_addc_u32 s17, s7, 0
	s_add_u32 s16, s16, s10
	s_addc_u32 s17, s17, 0
	s_add_u32 s16, s16, s11
	s_addc_u32 s17, s17, 0
	s_mov_b64 s[24:25], s[12:13]
	global_load_dwordx4 v[64:67], v120, s[24:25]
	s_add_u32 s24, s24, 0x80000
	s_addc_u32 s25, s25, 0
	global_load_dwordx4 v[68:71], v120, s[24:25]
	s_add_u32 s24, s24, 0x80000
	s_addc_u32 s25, s25, 0
	global_load_dwordx4 v[72:75], v120, s[24:25]
	s_add_u32 s24, s24, 0x80000
	s_addc_u32 s25, s25, 0
	global_load_dwordx4 v[76:79], v120, s[24:25]
	s_add_u32 s24, s24, 0x80000
	s_addc_u32 s25, s25, 0
	global_load_dwordx4 v[80:83], v120, s[24:25]
	s_add_u32 s24, s24, 0x80000
	s_addc_u32 s25, s25, 0
	global_load_dwordx4 v[84:87], v120, s[24:25]
	s_add_u32 s24, s24, 0x80000
	s_addc_u32 s25, s25, 0
	global_load_dwordx4 v[88:91], v120, s[24:25]
	s_add_u32 s24, s24, 0x80000
	s_addc_u32 s25, s25, 0
	global_load_dwordx4 v[92:95], v120, s[24:25]
	s_mov_b64 s[24:25], s[14:15]
	global_load_dwordx4 v[96:99], v121, s[24:25]
	s_add_u32 s24, s24, 0x100000
	s_addc_u32 s25, s25, 0
	global_load_dwordx4 v[100:103], v121, s[24:25]
	s_add_u32 s24, s24, 0x100000
	s_addc_u32 s25, s25, 0
	global_load_dwordx4 v[104:107], v121, s[24:25]
	s_add_u32 s24, s24, 0x100000
	s_addc_u32 s25, s25, 0
	global_load_dwordx4 v[108:111], v121, s[24:25]
	s_add_u32 s12, s12, 0x400000
	s_addc_u32 s13, s13, 0
	s_add_u32 s14, s14, 0x400000
	s_addc_u32 s15, s15, 0
	v_cmp_gt_u32_e32 vcc, 32, v181
	s_and_saveexec_b64 s[26:27], vcc
	v_mov_b32_e32 v126, 0
	v_add_u32_e32 v127, 102400, v112
	ds_write_b32 v127, v126
	s_mov_b64 exec, s[26:27]
	s_mov_b64 exec, -1
	s_mov_b32 s28, 0
.Llr_sc:
	s_barrier
	s_waitcnt vmcnt(0)
	ds_write_b128 v118, v[64:67] offset:0
	ds_write_b128 v118, v[68:71] offset:8192
	ds_write_b128 v118, v[72:75] offset:16384
	ds_write_b128 v118, v[76:79] offset:24576
	ds_write_b128 v118, v[80:83] offset:32768
	ds_write_b128 v118, v[84:87] offset:40960
	ds_write_b128 v118, v[88:91] offset:49152
	ds_write_b128 v118, v[92:95] offset:57344
	ds_write_b128 v119, v[96:99] offset:0
	ds_write_b128 v119, v[100:103] offset:8192
	ds_write_b128 v119, v[104:107] offset:16384
	ds_write_b128 v119, v[108:111] offset:24576
	s_waitcnt lgkmcnt(0)
	s_barrier
	s_cmp_eq_u32 s28, 7
	s_cbranch_scc1 .Llr_noload
	s_mov_b64 s[24:25], s[12:13]
	global_load_dwordx4 v[64:67], v120, s[24:25]
	s_add_u32 s24, s24, 0x80000
	s_addc_u32 s25, s25, 0
	global_load_dwordx4 v[68:71], v120, s[24:25]
	s_add_u32 s24, s24, 0x80000
	s_addc_u32 s25, s25, 0
	global_load_dwordx4 v[72:75], v120, s[24:25]
	s_add_u32 s24, s24, 0x80000
	s_addc_u32 s25, s25, 0
	global_load_dwordx4 v[76:79], v120, s[24:25]
	s_add_u32 s24, s24, 0x80000
	s_addc_u32 s25, s25, 0
	global_load_dwordx4 v[80:83], v120, s[24:25]
	s_add_u32 s24, s24, 0x80000
	s_addc_u32 s25, s25, 0
	global_load_dwordx4 v[84:87], v120, s[24:25]
	s_add_u32 s24, s24, 0x80000
	s_addc_u32 s25, s25, 0
	global_load_dwordx4 v[88:91], v120, s[24:25]
	s_add_u32 s24, s24, 0x80000
	s_addc_u32 s25, s25, 0
	global_load_dwordx4 v[92:95], v120, s[24:25]
	s_mov_b64 s[24:25], s[14:15]
	global_load_dwordx4 v[96:99], v121, s[24:25]
	s_add_u32 s24, s24, 0x100000
	s_addc_u32 s25, s25, 0
	global_load_dwordx4 v[100:103], v121, s[24:25]
	s_add_u32 s24, s24, 0x100000
	s_addc_u32 s25, s25, 0
	global_load_dwordx4 v[104:107], v121, s[24:25]
	s_add_u32 s24, s24, 0x100000
	s_addc_u32 s25, s25, 0
	global_load_dwordx4 v[108:111], v121, s[24:25]
	s_add_u32 s12, s12, 0x400000
	s_addc_u32 s13, s13, 0
	s_add_u32 s14, s14, 0x400000
	s_addc_u32 s15, s15, 0
; DI void phase_lru_scan(const Params& p, LAS unsigned char* lds) {
;     ...
;             float L = 0.f, H = 0.f;
; #pragma unroll 8
;             for (int t = 0; t < 32; ++t) { const unsigned w = tile[(seg * 32 + t) * 32 + chl]; const float la = __uint_as_float(w << 16); H = __expf(la) * H + __uint_as_float(w & 0xffff0000u); L += la; }
.Llr_noload:
	ds_read_b32 v0, v114 offset:0
	ds_read_b32 v1, v114 offset:128
	ds_read_b32 v2, v114 offset:256
	ds_read_b32 v3, v114 offset:384
	ds_read_b32 v4, v114 offset:512
	ds_read_b32 v5, v114 offset:640
	ds_read_b32 v6, v114 offset:768
	ds_read_b32 v7, v114 offset:896
	ds_read_b32 v8, v114 offset:1024
	ds_read_b32 v9, v114 offset:1152
	ds_read_b32 v10, v114 offset:1280
	ds_read_b32 v11, v114 offset:1408
	ds_read_b32 v12, v114 offset:1536
	ds_read_b32 v13, v114 offset:1664
	ds_read_b32 v14, v114 offset:1792
	ds_read_b32 v15, v114 offset:1920
	v_mov_b32_e32 v124, 0
	v_mov_b32_e32 v125, 0
	s_waitcnt lgkmcnt(0)
	v_lshlrev_b32_e32 v126, 16, v0
	v_mul_f32_e32 v32, 0x3fb8aa3b, v126
	v_exp_f32_e32 v32, v32
	v_add_f32_e32 v124, v124, v126
	v_and_b32_e32 v127, 0xffff0000, v0
	v_fma_f32 v125, v32, v125, v127
	v_lshlrev_b32_e32 v126, 16, v1
	v_mul_f32_e32 v33, 0x3fb8aa3b, v126
	v_exp_f32_e32 v33, v33
	v_add_f32_e32 v124, v124, v126
	v_and_b32_e32 v127, 0xffff0000, v1
	v_fma_f32 v125, v33, v125, v127
	v_lshlrev_b32_e32 v126, 16, v2
	v_mul_f32_e32 v34, 0x3fb8aa3b, v126
	v_exp_f32_e32 v34, v34
	v_add_f32_e32 v124, v124, v126
	v_and_b32_e32 v127, 0xffff0000, v2
	v_fma_f32 v125, v34, v125, v127
	v_lshlrev_b32_e32 v126, 16, v3
	v_mul_f32_e32 v35, 0x3fb8aa3b, v126
	v_exp_f32_e32 v35, v35
	v_add_f32_e32 v124, v124, v126
	v_and_b32_e32 v127, 0xffff0000, v3
	v_fma_f32 v125, v35, v125, v127
	v_lshlrev_b32_e32 v126, 16, v4
	v_mul_f32_e32 v36, 0x3fb8aa3b, v126
	v_exp_f32_e32 v36, v36
	v_add_f32_e32 v124, v124, v126
	v_and_b32_e32 v127, 0xffff0000, v4
	v_fma_f32 v125, v36, v125, v127
	v_lshlrev_b32_e32 v126, 16, v5
	v_mul_f32_e32 v37, 0x3fb8aa3b, v126
	v_exp_f32_e32 v37, v37
	v_add_f32_e32 v124, v124, v126
	v_and_b32_e32 v127, 0xffff0000, v5
	v_fma_f32 v125, v37, v125, v127
	v_lshlrev_b32_e32 v126, 16, v6
	v_mul_f32_e32 v38, 0x3fb8aa3b, v126
	v_exp_f32_e32 v38, v38
	v_add_f32_e32 v124, v124, v126
	v_and_b32_e32 v127, 0xffff0000, v6
	v_fma_f32 v125, v38, v125, v127
	v_lshlrev_b32_e32 v126, 16, v7
	v_mul_f32_e32 v39, 0x3fb8aa3b, v126
	v_exp_f32_e32 v39, v39
	v_add_f32_e32 v124, v124, v126
	v_and_b32_e32 v127, 0xffff0000, v7
	v_fma_f32 v125, v39, v125, v127
	v_lshlrev_b32_e32 v126, 16, v8
	v_mul_f32_e32 v40, 0x3fb8aa3b, v126
	v_exp_f32_e32 v40, v40
	v_add_f32_e32 v124, v124, v126
	v_and_b32_e32 v127, 0xffff0000, v8
	v_fma_f32 v125, v40, v125, v127
	v_lshlrev_b32_e32 v126, 16, v9
	v_mul_f32_e32 v41, 0x3fb8aa3b, v126
	v_exp_f32_e32 v41, v41
	v_add_f32_e32 v124, v124, v126
	v_and_b32_e32 v127, 0xffff0000, v9
	v_fma_f32 v125, v41, v125, v127
	v_lshlrev_b32_e32 v126, 16, v10
	v_mul_f32_e32 v42, 0x3fb8aa3b, v126
	v_exp_f32_e32 v42, v42
	v_add_f32_e32 v124, v124, v126
	v_and_b32_e32 v127, 0xffff0000, v10
	v_fma_f32 v125, v42, v125, v127
	v_lshlrev_b32_e32 v126, 16, v11
	v_mul_f32_e32 v43, 0x3fb8aa3b, v126
	v_exp_f32_e32 v43, v43
	v_add_f32_e32 v124, v124, v126
	v_and_b32_e32 v127, 0xffff0000, v11
	v_fma_f32 v125, v43, v125, v127
	v_lshlrev_b32_e32 v126, 16, v12
	v_mul_f32_e32 v44, 0x3fb8aa3b, v126
	v_exp_f32_e32 v44, v44
	v_add_f32_e32 v124, v124, v126
	v_and_b32_e32 v127, 0xffff0000, v12
	v_fma_f32 v125, v44, v125, v127
	v_lshlrev_b32_e32 v126, 16, v13
	v_mul_f32_e32 v45, 0x3fb8aa3b, v126
	v_exp_f32_e32 v45, v45
	v_add_f32_e32 v124, v124, v126
	v_and_b32_e32 v127, 0xffff0000, v13
	v_fma_f32 v125, v45, v125, v127
	v_lshlrev_b32_e32 v126, 16, v14
	v_mul_f32_e32 v46, 0x3fb8aa3b, v126
	v_exp_f32_e32 v46, v46
	v_add_f32_e32 v124, v124, v126
	v_and_b32_e32 v127, 0xffff0000, v14
	v_fma_f32 v125, v46, v125, v127
	v_lshlrev_b32_e32 v126, 16, v15
	v_mul_f32_e32 v47, 0x3fb8aa3b, v126
	v_exp_f32_e32 v47, v47
	v_add_f32_e32 v124, v124, v126
	v_and_b32_e32 v127, 0xffff0000, v15
	v_fma_f32 v125, v47, v125, v127
	ds_read_b32 v16, v114 offset:2048
	ds_read_b32 v17, v114 offset:2176
	ds_read_b32 v18, v114 offset:2304
	ds_read_b32 v19, v114 offset:2432
	ds_read_b32 v20, v114 offset:2560
	ds_read_b32 v21, v114 offset:2688
	ds_read_b32 v22, v114 offset:2816
	ds_read_b32 v23, v114 offset:2944
	ds_read_b32 v24, v114 offset:3072
	ds_read_b32 v25, v114 offset:3200
	ds_read_b32 v26, v114 offset:3328
	ds_read_b32 v27, v114 offset:3456
	ds_read_b32 v28, v114 offset:3584
	ds_read_b32 v29, v114 offset:3712
	ds_read_b32 v30, v114 offset:3840
	ds_read_b32 v31, v114 offset:3968
	s_waitcnt lgkmcnt(0)
; DI void phase_lru_scan(const Params& p, LAS unsigned char* lds) {
;     ...
;             for (int t = 0; t < 32; ++t) { const unsigned w = tile[(seg * 32 + t) * 32 + chl]; const float la = __uint_as_float(w << 16); H = __expf(la) * H + __uint_as_float(w & 0xffff0000u); L += la; }
;             sP[tid] = __expf(L); sH[tid] = H;
;             __syncthreads();
;             float hc = sC[chl];
;             for (int sg = 0; sg < seg; ++sg) hc = sP[sg * 32 + chl] * hc + sH[sg * 32 + chl];
	v_lshlrev_b32_e32 v126, 16, v16
	v_mul_f32_e32 v48, 0x3fb8aa3b, v126
	v_exp_f32_e32 v48, v48
	v_add_f32_e32 v124, v124, v126
	v_and_b32_e32 v127, 0xffff0000, v16
	v_fma_f32 v125, v48, v125, v127
	v_lshlrev_b32_e32 v126, 16, v17
	v_mul_f32_e32 v49, 0x3fb8aa3b, v126
	v_exp_f32_e32 v49, v49
	v_add_f32_e32 v124, v124, v126
	v_and_b32_e32 v127, 0xffff0000, v17
	v_fma_f32 v125, v49, v125, v127
	v_lshlrev_b32_e32 v126, 16, v18
	v_mul_f32_e32 v50, 0x3fb8aa3b, v126
	v_exp_f32_e32 v50, v50
	v_add_f32_e32 v124, v124, v126
	v_and_b32_e32 v127, 0xffff0000, v18
	v_fma_f32 v125, v50, v125, v127
	v_lshlrev_b32_e32 v126, 16, v19
	v_mul_f32_e32 v51, 0x3fb8aa3b, v126
	v_exp_f32_e32 v51, v51
	v_add_f32_e32 v124, v124, v126
	v_and_b32_e32 v127, 0xffff0000, v19
	v_fma_f32 v125, v51, v125, v127
	v_lshlrev_b32_e32 v126, 16, v20
	v_mul_f32_e32 v52, 0x3fb8aa3b, v126
	v_exp_f32_e32 v52, v52
	v_add_f32_e32 v124, v124, v126
	v_and_b32_e32 v127, 0xffff0000, v20
	v_fma_f32 v125, v52, v125, v127
	v_lshlrev_b32_e32 v126, 16, v21
	v_mul_f32_e32 v53, 0x3fb8aa3b, v126
	v_exp_f32_e32 v53, v53
	v_add_f32_e32 v124, v124, v126
	v_and_b32_e32 v127, 0xffff0000, v21
	v_fma_f32 v125, v53, v125, v127
	v_lshlrev_b32_e32 v126, 16, v22
	v_mul_f32_e32 v54, 0x3fb8aa3b, v126
	v_exp_f32_e32 v54, v54
	v_add_f32_e32 v124, v124, v126
	v_and_b32_e32 v127, 0xffff0000, v22
	v_fma_f32 v125, v54, v125, v127
	v_lshlrev_b32_e32 v126, 16, v23
	v_mul_f32_e32 v55, 0x3fb8aa3b, v126
	v_exp_f32_e32 v55, v55
	v_add_f32_e32 v124, v124, v126
	v_and_b32_e32 v127, 0xffff0000, v23
	v_fma_f32 v125, v55, v125, v127
	v_lshlrev_b32_e32 v126, 16, v24
	v_mul_f32_e32 v56, 0x3fb8aa3b, v126
	v_exp_f32_e32 v56, v56
	v_add_f32_e32 v124, v124, v126
	v_and_b32_e32 v127, 0xffff0000, v24
	v_fma_f32 v125, v56, v125, v127
	v_lshlrev_b32_e32 v126, 16, v25
	v_mul_f32_e32 v57, 0x3fb8aa3b, v126
	v_exp_f32_e32 v57, v57
	v_add_f32_e32 v124, v124, v126
	v_and_b32_e32 v127, 0xffff0000, v25
	v_fma_f32 v125, v57, v125, v127
	v_lshlrev_b32_e32 v126, 16, v26
	v_mul_f32_e32 v58, 0x3fb8aa3b, v126
	v_exp_f32_e32 v58, v58
	v_add_f32_e32 v124, v124, v126
	v_and_b32_e32 v127, 0xffff0000, v26
	v_fma_f32 v125, v58, v125, v127
	v_lshlrev_b32_e32 v126, 16, v27
	v_mul_f32_e32 v59, 0x3fb8aa3b, v126
	v_exp_f32_e32 v59, v59
	v_add_f32_e32 v124, v124, v126
	v_and_b32_e32 v127, 0xffff0000, v27
	v_fma_f32 v125, v59, v125, v127
	v_lshlrev_b32_e32 v126, 16, v28
	v_mul_f32_e32 v60, 0x3fb8aa3b, v126
	v_exp_f32_e32 v60, v60
	v_add_f32_e32 v124, v124, v126
	v_and_b32_e32 v127, 0xffff0000, v28
	v_fma_f32 v125, v60, v125, v127
	v_lshlrev_b32_e32 v126, 16, v29
	v_mul_f32_e32 v61, 0x3fb8aa3b, v126
	v_exp_f32_e32 v61, v61
	v_add_f32_e32 v124, v124, v126
	v_and_b32_e32 v127, 0xffff0000, v29
	v_fma_f32 v125, v61, v125, v127
	v_lshlrev_b32_e32 v126, 16, v30
	v_mul_f32_e32 v62, 0x3fb8aa3b, v126
	v_exp_f32_e32 v62, v62
	v_add_f32_e32 v124, v124, v126
	v_and_b32_e32 v127, 0xffff0000, v30
	v_fma_f32 v125, v62, v125, v127
	v_lshlrev_b32_e32 v126, 16, v31
	v_mul_f32_e32 v63, 0x3fb8aa3b, v126
	v_exp_f32_e32 v63, v63
	v_add_f32_e32 v124, v124, v126
	v_and_b32_e32 v127, 0xffff0000, v31
	v_fma_f32 v125, v63, v125, v127
	v_mul_f32_e32 v124, 0x3fb8aa3b, v124
	v_exp_f32_e32 v124, v124
	s_nop 0
	ds_write_b32 v116, v124
	ds_write_b32 v116, v125 offset:2048
	s_waitcnt lgkmcnt(0)
	s_barrier
	ds_read_b32 v123, v117 offset:4096
	ds_read_b32 v126, v117 offset:0
	ds_read_b32 v127, v117 offset:2048
	ds_read_b32 v128, v117 offset:128
	ds_read_b32 v129, v117 offset:2176
	ds_read_b32 v130, v117 offset:256
	ds_read_b32 v131, v117 offset:2304
	ds_read_b32 v132, v117 offset:384
	ds_read_b32 v133, v117 offset:2432
	ds_read_b32 v134, v117 offset:512
	ds_read_b32 v135, v117 offset:2560
	ds_read_b32 v136, v117 offset:640
	ds_read_b32 v137, v117 offset:2688
	ds_read_b32 v138, v117 offset:768
	ds_read_b32 v139, v117 offset:2816
	s_waitcnt lgkmcnt(0)
	v_cmp_lt_u32_e32 vcc, 0, v113
	v_fma_f32 v126, v126, v123, v127
	s_nop 0
	v_cndmask_b32_e32 v123, v123, v126, vcc
	v_cmp_lt_u32_e32 vcc, 1, v113
	v_fma_f32 v128, v128, v123, v129
	s_nop 0
	v_cndmask_b32_e32 v123, v123, v128, vcc
	v_cmp_lt_u32_e32 vcc, 2, v113
	v_fma_f32 v130, v130, v123, v131
	s_nop 0
	v_cndmask_b32_e32 v123, v123, v130, vcc
	v_cmp_lt_u32_e32 vcc, 3, v113
	v_fma_f32 v132, v132, v123, v133
	s_nop 0
	v_cndmask_b32_e32 v123, v123, v132, vcc
	v_cmp_lt_u32_e32 vcc, 4, v113
	v_fma_f32 v134, v134, v123, v135
	s_nop 0
	v_cndmask_b32_e32 v123, v123, v134, vcc
	v_cmp_lt_u32_e32 vcc, 5, v113
	v_fma_f32 v136, v136, v123, v137
	s_nop 0
	v_cndmask_b32_e32 v123, v123, v136, vcc
	v_cmp_lt_u32_e32 vcc, 6, v113
	v_fma_f32 v138, v138, v123, v139
	s_nop 0
	v_cndmask_b32_e32 v123, v123, v138, vcc
	ds_read_b32 v126, v117 offset:896
	ds_read_b32 v127, v117 offset:2944
	ds_read_b32 v128, v117 offset:1024
	ds_read_b32 v129, v117 offset:3072
	ds_read_b32 v130, v117 offset:1152
	ds_read_b32 v131, v117 offset:3200
	ds_read_b32 v132, v117 offset:1280
	ds_read_b32 v133, v117 offset:3328
	ds_read_b32 v134, v117 offset:1408
	ds_read_b32 v135, v117 offset:3456
	ds_read_b32 v136, v117 offset:1536
	ds_read_b32 v137, v117 offset:3584
	ds_read_b32 v138, v117 offset:1664
	ds_read_b32 v139, v117 offset:3712
	ds_read_b32 v140, v117 offset:1792
	ds_read_b32 v141, v117 offset:3840
	s_waitcnt lgkmcnt(0)
; DI float bf2f(bf16_t v) { return __uint_as_float((unsigned)v << 16); }
; DI bf16_t f2bf(float a) { return (bf16_t)(pk2(a, 0.f) & 0xffffu); }
; DI float silu(float x) { return x / (1.f + __expf(-x)); }
; DI void phase_lru_scan(const Params& p, LAS unsigned char* lds) {
;     ...
;             for (int sg = 0; sg < seg; ++sg) hc = sP[sg * 32 + chl] * hc + sH[sg * 32 + chl];
; #pragma unroll
;             for (int t = 0; t < 32; ++t) { const unsigned w = tile[(seg * 32 + t) * 32 + chl]; hc = __expf(__uint_as_float(w << 16)) * hc + __uint_as_float(w & 0xffff0000u);
;                 y[(r0 + t) * DM + ch] = f2bf(hc * silu(bf2f(gq[t]))); }
	v_cmp_lt_u32_e32 vcc, 7, v113
	v_fma_f32 v126, v126, v123, v127
	s_nop 0
	v_cndmask_b32_e32 v123, v123, v126, vcc
	v_cmp_lt_u32_e32 vcc, 8, v113
	v_fma_f32 v128, v128, v123, v129
	s_nop 0
	v_cndmask_b32_e32 v123, v123, v128, vcc
	v_cmp_lt_u32_e32 vcc, 9, v113
	v_fma_f32 v130, v130, v123, v131
	s_nop 0
	v_cndmask_b32_e32 v123, v123, v130, vcc
	v_cmp_lt_u32_e32 vcc, 10, v113
	v_fma_f32 v132, v132, v123, v133
	s_nop 0
	v_cndmask_b32_e32 v123, v123, v132, vcc
	v_cmp_lt_u32_e32 vcc, 11, v113
	v_fma_f32 v134, v134, v123, v135
	s_nop 0
	v_cndmask_b32_e32 v123, v123, v134, vcc
	v_cmp_lt_u32_e32 vcc, 12, v113
	v_fma_f32 v136, v136, v123, v137
	s_nop 0
	v_cndmask_b32_e32 v123, v123, v136, vcc
	v_cmp_lt_u32_e32 vcc, 13, v113
	v_fma_f32 v138, v138, v123, v139
	s_nop 0
	v_cndmask_b32_e32 v123, v123, v138, vcc
	v_cmp_lt_u32_e32 vcc, 14, v113
	v_fma_f32 v140, v140, v123, v141
	s_nop 0
	v_cndmask_b32_e32 v123, v123, v140, vcc
	ds_read_u16 v146, v115 offset:0
	ds_read_u16 v147, v115 offset:64
	ds_read_u16 v148, v115 offset:128
	ds_read_u16 v149, v115 offset:192
	ds_read_u16 v150, v115 offset:256
	ds_read_u16 v151, v115 offset:320
	ds_read_u16 v152, v115 offset:384
	ds_read_u16 v153, v115 offset:448
	ds_read_u16 v154, v115 offset:512
	ds_read_u16 v155, v115 offset:576
	ds_read_u16 v156, v115 offset:640
	ds_read_u16 v157, v115 offset:704
	ds_read_u16 v158, v115 offset:768
	ds_read_u16 v159, v115 offset:832
	ds_read_u16 v160, v115 offset:896
	ds_read_u16 v161, v115 offset:960
	s_waitcnt lgkmcnt(0)
	v_and_b32_e32 v126, 0xffff0000, v0
	v_fma_f32 v123, v32, v123, v126
	v_lshlrev_b32_e32 v146, 16, v146
	v_mul_f32_e32 v127, 0xbfb8aa3b, v146
	v_exp_f32_e32 v127, v127
	v_mul_f32_e32 v128, v123, v146
	v_add_f32_e32 v127, 1.0, v127
	v_rcp_f32_e32 v127, v127
	s_nop 0
	v_mul_f32_e32 v128, v128, v127
	v_cvt_pk_bf16_f32 v128, v128, v128
	ds_write_b16 v115, v128 offset:0
	v_and_b32_e32 v126, 0xffff0000, v1
	v_fma_f32 v123, v33, v123, v126
	v_lshlrev_b32_e32 v147, 16, v147
	v_mul_f32_e32 v127, 0xbfb8aa3b, v147
	v_exp_f32_e32 v127, v127
	v_mul_f32_e32 v128, v123, v147
	v_add_f32_e32 v127, 1.0, v127
	v_rcp_f32_e32 v127, v127
	s_nop 0
	v_mul_f32_e32 v128, v128, v127
	v_cvt_pk_bf16_f32 v128, v128, v128
	ds_write_b16 v115, v128 offset:64
	v_and_b32_e32 v126, 0xffff0000, v2
	v_fma_f32 v123, v34, v123, v126
	v_lshlrev_b32_e32 v148, 16, v148
	v_mul_f32_e32 v127, 0xbfb8aa3b, v148
	v_exp_f32_e32 v127, v127
	v_mul_f32_e32 v128, v123, v148
	v_add_f32_e32 v127, 1.0, v127
	v_rcp_f32_e32 v127, v127
	s_nop 0
	v_mul_f32_e32 v128, v128, v127
	v_cvt_pk_bf16_f32 v128, v128, v128
	ds_write_b16 v115, v128 offset:128
	v_and_b32_e32 v126, 0xffff0000, v3
	v_fma_f32 v123, v35, v123, v126
	v_lshlrev_b32_e32 v149, 16, v149
	v_mul_f32_e32 v127, 0xbfb8aa3b, v149
	v_exp_f32_e32 v127, v127
	v_mul_f32_e32 v128, v123, v149
	v_add_f32_e32 v127, 1.0, v127
	v_rcp_f32_e32 v127, v127
	s_nop 0
	v_mul_f32_e32 v128, v128, v127
	v_cvt_pk_bf16_f32 v128, v128, v128
	ds_write_b16 v115, v128 offset:192
	v_and_b32_e32 v126, 0xffff0000, v4
	v_fma_f32 v123, v36, v123, v126
	v_lshlrev_b32_e32 v150, 16, v150
	v_mul_f32_e32 v127, 0xbfb8aa3b, v150
	v_exp_f32_e32 v127, v127
	v_mul_f32_e32 v128, v123, v150
	v_add_f32_e32 v127, 1.0, v127
	v_rcp_f32_e32 v127, v127
	s_nop 0
	v_mul_f32_e32 v128, v128, v127
	v_cvt_pk_bf16_f32 v128, v128, v128
	ds_write_b16 v115, v128 offset:256
	v_and_b32_e32 v126, 0xffff0000, v5
	v_fma_f32 v123, v37, v123, v126
	v_lshlrev_b32_e32 v151, 16, v151
	v_mul_f32_e32 v127, 0xbfb8aa3b, v151
	v_exp_f32_e32 v127, v127
	v_mul_f32_e32 v128, v123, v151
	v_add_f32_e32 v127, 1.0, v127
	v_rcp_f32_e32 v127, v127
	s_nop 0
	v_mul_f32_e32 v128, v128, v127
	v_cvt_pk_bf16_f32 v128, v128, v128
	ds_write_b16 v115, v128 offset:320
	v_and_b32_e32 v126, 0xffff0000, v6
	v_fma_f32 v123, v38, v123, v126
	v_lshlrev_b32_e32 v152, 16, v152
	v_mul_f32_e32 v127, 0xbfb8aa3b, v152
	v_exp_f32_e32 v127, v127
	v_mul_f32_e32 v128, v123, v152
	v_add_f32_e32 v127, 1.0, v127
	v_rcp_f32_e32 v127, v127
	s_nop 0
	v_mul_f32_e32 v128, v128, v127
	v_cvt_pk_bf16_f32 v128, v128, v128
	ds_write_b16 v115, v128 offset:384
	v_and_b32_e32 v126, 0xffff0000, v7
	v_fma_f32 v123, v39, v123, v126
	v_lshlrev_b32_e32 v153, 16, v153
	v_mul_f32_e32 v127, 0xbfb8aa3b, v153
	v_exp_f32_e32 v127, v127
	v_mul_f32_e32 v128, v123, v153
	v_add_f32_e32 v127, 1.0, v127
	v_rcp_f32_e32 v127, v127
	s_nop 0
	v_mul_f32_e32 v128, v128, v127
	v_cvt_pk_bf16_f32 v128, v128, v128
	ds_write_b16 v115, v128 offset:448
	v_and_b32_e32 v126, 0xffff0000, v8
	v_fma_f32 v123, v40, v123, v126
	v_lshlrev_b32_e32 v154, 16, v154
	v_mul_f32_e32 v127, 0xbfb8aa3b, v154
	v_exp_f32_e32 v127, v127
	v_mul_f32_e32 v128, v123, v154
	v_add_f32_e32 v127, 1.0, v127
	v_rcp_f32_e32 v127, v127
	s_nop 0
	v_mul_f32_e32 v128, v128, v127
	v_cvt_pk_bf16_f32 v128, v128, v128
	ds_write_b16 v115, v128 offset:512
	v_and_b32_e32 v126, 0xffff0000, v9
	v_fma_f32 v123, v41, v123, v126
	v_lshlrev_b32_e32 v155, 16, v155
	v_mul_f32_e32 v127, 0xbfb8aa3b, v155
	v_exp_f32_e32 v127, v127
	v_mul_f32_e32 v128, v123, v155
	v_add_f32_e32 v127, 1.0, v127
	v_rcp_f32_e32 v127, v127
	s_nop 0
	v_mul_f32_e32 v128, v128, v127
	v_cvt_pk_bf16_f32 v128, v128, v128
	ds_write_b16 v115, v128 offset:576
	v_and_b32_e32 v126, 0xffff0000, v10
	v_fma_f32 v123, v42, v123, v126
	v_lshlrev_b32_e32 v156, 16, v156
	v_mul_f32_e32 v127, 0xbfb8aa3b, v156
	v_exp_f32_e32 v127, v127
	v_mul_f32_e32 v128, v123, v156
	v_add_f32_e32 v127, 1.0, v127
	v_rcp_f32_e32 v127, v127
	s_nop 0
	v_mul_f32_e32 v128, v128, v127
	v_cvt_pk_bf16_f32 v128, v128, v128
	ds_write_b16 v115, v128 offset:640
	v_and_b32_e32 v126, 0xffff0000, v11
	v_fma_f32 v123, v43, v123, v126
; DI float bf2f(bf16_t v) { return __uint_as_float((unsigned)v << 16); }
; DI bf16_t f2bf(float a) { return (bf16_t)(pk2(a, 0.f) & 0xffffu); }
; DI float silu(float x) { return x / (1.f + __expf(-x)); }
; DI void phase_lru_scan(const Params& p, LAS unsigned char* lds) {
;     ...
;             for (int t = 0; t < 32; ++t) { const unsigned w = tile[(seg * 32 + t) * 32 + chl]; hc = __expf(__uint_as_float(w << 16)) * hc + __uint_as_float(w & 0xffff0000u);
;                 y[(r0 + t) * DM + ch] = f2bf(hc * silu(bf2f(gq[t]))); }
	v_lshlrev_b32_e32 v157, 16, v157
	v_mul_f32_e32 v127, 0xbfb8aa3b, v157
	v_exp_f32_e32 v127, v127
	v_mul_f32_e32 v128, v123, v157
	v_add_f32_e32 v127, 1.0, v127
	v_rcp_f32_e32 v127, v127
	s_nop 0
	v_mul_f32_e32 v128, v128, v127
	v_cvt_pk_bf16_f32 v128, v128, v128
	ds_write_b16 v115, v128 offset:704
	v_and_b32_e32 v126, 0xffff0000, v12
	v_fma_f32 v123, v44, v123, v126
	v_lshlrev_b32_e32 v158, 16, v158
	v_mul_f32_e32 v127, 0xbfb8aa3b, v158
	v_exp_f32_e32 v127, v127
	v_mul_f32_e32 v128, v123, v158
	v_add_f32_e32 v127, 1.0, v127
	v_rcp_f32_e32 v127, v127
	s_nop 0
	v_mul_f32_e32 v128, v128, v127
	v_cvt_pk_bf16_f32 v128, v128, v128
	ds_write_b16 v115, v128 offset:768
	v_and_b32_e32 v126, 0xffff0000, v13
	v_fma_f32 v123, v45, v123, v126
	v_lshlrev_b32_e32 v159, 16, v159
	v_mul_f32_e32 v127, 0xbfb8aa3b, v159
	v_exp_f32_e32 v127, v127
	v_mul_f32_e32 v128, v123, v159
	v_add_f32_e32 v127, 1.0, v127
	v_rcp_f32_e32 v127, v127
	s_nop 0
	v_mul_f32_e32 v128, v128, v127
	v_cvt_pk_bf16_f32 v128, v128, v128
	ds_write_b16 v115, v128 offset:832
	v_and_b32_e32 v126, 0xffff0000, v14
	v_fma_f32 v123, v46, v123, v126
	v_lshlrev_b32_e32 v160, 16, v160
	v_mul_f32_e32 v127, 0xbfb8aa3b, v160
	v_exp_f32_e32 v127, v127
	v_mul_f32_e32 v128, v123, v160
	v_add_f32_e32 v127, 1.0, v127
	v_rcp_f32_e32 v127, v127
	s_nop 0
	v_mul_f32_e32 v128, v128, v127
	v_cvt_pk_bf16_f32 v128, v128, v128
	ds_write_b16 v115, v128 offset:896
	v_and_b32_e32 v126, 0xffff0000, v15
	v_fma_f32 v123, v47, v123, v126
	v_lshlrev_b32_e32 v161, 16, v161
	v_mul_f32_e32 v127, 0xbfb8aa3b, v161
	v_exp_f32_e32 v127, v127
	v_mul_f32_e32 v128, v123, v161
	v_add_f32_e32 v127, 1.0, v127
	v_rcp_f32_e32 v127, v127
	s_nop 0
	v_mul_f32_e32 v128, v128, v127
	v_cvt_pk_bf16_f32 v128, v128, v128
	ds_write_b16 v115, v128 offset:960
	ds_read_u16 v146, v115 offset:1024
	ds_read_u16 v147, v115 offset:1088
	ds_read_u16 v148, v115 offset:1152
	ds_read_u16 v149, v115 offset:1216
	ds_read_u16 v150, v115 offset:1280
	ds_read_u16 v151, v115 offset:1344
	ds_read_u16 v152, v115 offset:1408
	ds_read_u16 v153, v115 offset:1472
	ds_read_u16 v154, v115 offset:1536
	ds_read_u16 v155, v115 offset:1600
	ds_read_u16 v156, v115 offset:1664
	ds_read_u16 v157, v115 offset:1728
	ds_read_u16 v158, v115 offset:1792
	ds_read_u16 v159, v115 offset:1856
	ds_read_u16 v160, v115 offset:1920
	ds_read_u16 v161, v115 offset:1984
	s_waitcnt lgkmcnt(0)
	v_and_b32_e32 v126, 0xffff0000, v16
	v_fma_f32 v123, v48, v123, v126
	v_lshlrev_b32_e32 v146, 16, v146
	v_mul_f32_e32 v127, 0xbfb8aa3b, v146
	v_exp_f32_e32 v127, v127
	v_mul_f32_e32 v128, v123, v146
	v_add_f32_e32 v127, 1.0, v127
	v_rcp_f32_e32 v127, v127
	s_nop 0
	v_mul_f32_e32 v128, v128, v127
	v_cvt_pk_bf16_f32 v128, v128, v128
	ds_write_b16 v115, v128 offset:1024
	v_and_b32_e32 v126, 0xffff0000, v17
	v_fma_f32 v123, v49, v123, v126
	v_lshlrev_b32_e32 v147, 16, v147
	v_mul_f32_e32 v127, 0xbfb8aa3b, v147
	v_exp_f32_e32 v127, v127
	v_mul_f32_e32 v128, v123, v147
	v_add_f32_e32 v127, 1.0, v127
	v_rcp_f32_e32 v127, v127
	s_nop 0
	v_mul_f32_e32 v128, v128, v127
	v_cvt_pk_bf16_f32 v128, v128, v128
	ds_write_b16 v115, v128 offset:1088
	v_and_b32_e32 v126, 0xffff0000, v18
	v_fma_f32 v123, v50, v123, v126
	v_lshlrev_b32_e32 v148, 16, v148
	v_mul_f32_e32 v127, 0xbfb8aa3b, v148
	v_exp_f32_e32 v127, v127
	v_mul_f32_e32 v128, v123, v148
	v_add_f32_e32 v127, 1.0, v127
	v_rcp_f32_e32 v127, v127
	s_nop 0
	v_mul_f32_e32 v128, v128, v127
	v_cvt_pk_bf16_f32 v128, v128, v128
	ds_write_b16 v115, v128 offset:1152
	v_and_b32_e32 v126, 0xffff0000, v19
	v_fma_f32 v123, v51, v123, v126
	v_lshlrev_b32_e32 v149, 16, v149
	v_mul_f32_e32 v127, 0xbfb8aa3b, v149
	v_exp_f32_e32 v127, v127
	v_mul_f32_e32 v128, v123, v149
	v_add_f32_e32 v127, 1.0, v127
	v_rcp_f32_e32 v127, v127
	s_nop 0
	v_mul_f32_e32 v128, v128, v127
	v_cvt_pk_bf16_f32 v128, v128, v128
	ds_write_b16 v115, v128 offset:1216
	v_and_b32_e32 v126, 0xffff0000, v20
	v_fma_f32 v123, v52, v123, v126
	v_lshlrev_b32_e32 v150, 16, v150
	v_mul_f32_e32 v127, 0xbfb8aa3b, v150
	v_exp_f32_e32 v127, v127
	v_mul_f32_e32 v128, v123, v150
	v_add_f32_e32 v127, 1.0, v127
	v_rcp_f32_e32 v127, v127
	s_nop 0
	v_mul_f32_e32 v128, v128, v127
	v_cvt_pk_bf16_f32 v128, v128, v128
	ds_write_b16 v115, v128 offset:1280
	v_and_b32_e32 v126, 0xffff0000, v21
	v_fma_f32 v123, v53, v123, v126
	v_lshlrev_b32_e32 v151, 16, v151
	v_mul_f32_e32 v127, 0xbfb8aa3b, v151
	v_exp_f32_e32 v127, v127
	v_mul_f32_e32 v128, v123, v151
	v_add_f32_e32 v127, 1.0, v127
	v_rcp_f32_e32 v127, v127
	s_nop 0
	v_mul_f32_e32 v128, v128, v127
	v_cvt_pk_bf16_f32 v128, v128, v128
	ds_write_b16 v115, v128 offset:1344
	v_and_b32_e32 v126, 0xffff0000, v22
	v_fma_f32 v123, v54, v123, v126
	v_lshlrev_b32_e32 v152, 16, v152
	v_mul_f32_e32 v127, 0xbfb8aa3b, v152
	v_exp_f32_e32 v127, v127
	v_mul_f32_e32 v128, v123, v152
	v_add_f32_e32 v127, 1.0, v127
	v_rcp_f32_e32 v127, v127
	s_nop 0
	v_mul_f32_e32 v128, v128, v127
	v_cvt_pk_bf16_f32 v128, v128, v128
	ds_write_b16 v115, v128 offset:1408
	v_and_b32_e32 v126, 0xffff0000, v23
	v_fma_f32 v123, v55, v123, v126
	v_lshlrev_b32_e32 v153, 16, v153
	v_mul_f32_e32 v127, 0xbfb8aa3b, v153
	v_exp_f32_e32 v127, v127
	v_mul_f32_e32 v128, v123, v153
	v_add_f32_e32 v127, 1.0, v127
; #define LAS __attribute__((address_space(3)))
; DI int otid() { int t = threadIdx.x; asm volatile("" : "+v"(t)); return t; }
; DI float bf2f(bf16_t v) { return __uint_as_float((unsigned)v << 16); }
; DI bf16_t f2bf(float a) { return (bf16_t)(pk2(a, 0.f) & 0xffffu); }
; DI float silu(float x) { return x / (1.f + __expf(-x)); }
; DI void phase_lru_scan(const Params& p, LAS unsigned char* lds) {
;     const unsigned* ax = (const unsigned*)(p.ws + ACT + 128 * MiB); const bf16_t* big = (const bf16_t*)(p.ws + ACT);
;     bf16_t* y = (bf16_t*)(p.ws + HBUF);
;     LAS unsigned* tile = (LAS unsigned*)lds;
;     LAS float* sP = (LAS float*)(lds + 65536); LAS float* sH = sP + 512; LAS float* sC = sH + 512;
;     const int tid = otid(), seg = tid >> 5, chl = tid & 31;
;     for (int u = blockIdx.x; u < 256; u += gridDim.x) {
;         const int b = u >> 6, ch = (u & 63) * 32 + chl;
;         const size_t rowbase = (size_t)b * SEQ;
;         unsigned pre[32];
; #pragma unroll
;         for (int i = 0; i < 32; ++i) pre[i] = ax[(rowbase + seg + 16 * i) * DM + ch];
;     ...
;             for (int t = 0; t < 32; ++t) { const unsigned w = tile[(seg * 32 + t) * 32 + chl]; hc = __expf(__uint_as_float(w << 16)) * hc + __uint_as_float(w & 0xffff0000u);
;                 y[(r0 + t) * DM + ch] = f2bf(hc * silu(bf2f(gq[t]))); }
;             __syncthreads();
;             if (seg == 15) sC[chl] = hc;
;         }
;     }
	v_rcp_f32_e32 v127, v127
	s_nop 0
	v_mul_f32_e32 v128, v128, v127
	v_cvt_pk_bf16_f32 v128, v128, v128
	ds_write_b16 v115, v128 offset:1472
	v_and_b32_e32 v126, 0xffff0000, v24
	v_fma_f32 v123, v56, v123, v126
	v_lshlrev_b32_e32 v154, 16, v154
	v_mul_f32_e32 v127, 0xbfb8aa3b, v154
	v_exp_f32_e32 v127, v127
	v_mul_f32_e32 v128, v123, v154
	v_add_f32_e32 v127, 1.0, v127
	v_rcp_f32_e32 v127, v127
	s_nop 0
	v_mul_f32_e32 v128, v128, v127
	v_cvt_pk_bf16_f32 v128, v128, v128
	ds_write_b16 v115, v128 offset:1536
	v_and_b32_e32 v126, 0xffff0000, v25
	v_fma_f32 v123, v57, v123, v126
	v_lshlrev_b32_e32 v155, 16, v155
	v_mul_f32_e32 v127, 0xbfb8aa3b, v155
	v_exp_f32_e32 v127, v127
	v_mul_f32_e32 v128, v123, v155
	v_add_f32_e32 v127, 1.0, v127
	v_rcp_f32_e32 v127, v127
	s_nop 0
	v_mul_f32_e32 v128, v128, v127
	v_cvt_pk_bf16_f32 v128, v128, v128
	ds_write_b16 v115, v128 offset:1600
	v_and_b32_e32 v126, 0xffff0000, v26
	v_fma_f32 v123, v58, v123, v126
	v_lshlrev_b32_e32 v156, 16, v156
	v_mul_f32_e32 v127, 0xbfb8aa3b, v156
	v_exp_f32_e32 v127, v127
	v_mul_f32_e32 v128, v123, v156
	v_add_f32_e32 v127, 1.0, v127
	v_rcp_f32_e32 v127, v127
	s_nop 0
	v_mul_f32_e32 v128, v128, v127
	v_cvt_pk_bf16_f32 v128, v128, v128
	ds_write_b16 v115, v128 offset:1664
	v_and_b32_e32 v126, 0xffff0000, v27
	v_fma_f32 v123, v59, v123, v126
	v_lshlrev_b32_e32 v157, 16, v157
	v_mul_f32_e32 v127, 0xbfb8aa3b, v157
	v_exp_f32_e32 v127, v127
	v_mul_f32_e32 v128, v123, v157
	v_add_f32_e32 v127, 1.0, v127
	v_rcp_f32_e32 v127, v127
	s_nop 0
	v_mul_f32_e32 v128, v128, v127
	v_cvt_pk_bf16_f32 v128, v128, v128
	ds_write_b16 v115, v128 offset:1728
	v_and_b32_e32 v126, 0xffff0000, v28
	v_fma_f32 v123, v60, v123, v126
	v_lshlrev_b32_e32 v158, 16, v158
	v_mul_f32_e32 v127, 0xbfb8aa3b, v158
	v_exp_f32_e32 v127, v127
	v_mul_f32_e32 v128, v123, v158
	v_add_f32_e32 v127, 1.0, v127
	v_rcp_f32_e32 v127, v127
	s_nop 0
	v_mul_f32_e32 v128, v128, v127
	v_cvt_pk_bf16_f32 v128, v128, v128
	ds_write_b16 v115, v128 offset:1792
	v_and_b32_e32 v126, 0xffff0000, v29
	v_fma_f32 v123, v61, v123, v126
	v_lshlrev_b32_e32 v159, 16, v159
	v_mul_f32_e32 v127, 0xbfb8aa3b, v159
	v_exp_f32_e32 v127, v127
	v_mul_f32_e32 v128, v123, v159
	v_add_f32_e32 v127, 1.0, v127
	v_rcp_f32_e32 v127, v127
	s_nop 0
	v_mul_f32_e32 v128, v128, v127
	v_cvt_pk_bf16_f32 v128, v128, v128
	ds_write_b16 v115, v128 offset:1856
	v_and_b32_e32 v126, 0xffff0000, v30
	v_fma_f32 v123, v62, v123, v126
	v_lshlrev_b32_e32 v160, 16, v160
	v_mul_f32_e32 v127, 0xbfb8aa3b, v160
	v_exp_f32_e32 v127, v127
	v_mul_f32_e32 v128, v123, v160
	v_add_f32_e32 v127, 1.0, v127
	v_rcp_f32_e32 v127, v127
	s_nop 0
	v_mul_f32_e32 v128, v128, v127
	v_cvt_pk_bf16_f32 v128, v128, v128
	ds_write_b16 v115, v128 offset:1920
	v_and_b32_e32 v126, 0xffff0000, v31
	v_fma_f32 v123, v63, v123, v126
	v_lshlrev_b32_e32 v161, 16, v161
	v_mul_f32_e32 v127, 0xbfb8aa3b, v161
	v_exp_f32_e32 v127, v127
	v_mul_f32_e32 v128, v123, v161
	v_add_f32_e32 v127, 1.0, v127
	v_rcp_f32_e32 v127, v127
	s_nop 0
	v_mul_f32_e32 v128, v128, v127
	v_cvt_pk_bf16_f32 v128, v128, v128
	ds_write_b16 v115, v128 offset:1984
	s_waitcnt lgkmcnt(0)
	s_barrier
	v_cmp_eq_u32_e32 vcc, 15, v113
	s_and_saveexec_b64 s[26:27], vcc
	v_add_u32_e32 v127, 102400, v112
	ds_write_b32 v127, v123
	s_mov_b64 exec, -1
	ds_read_b128 v[130:133], v119 offset:0
	ds_read_b128 v[134:137], v119 offset:8192
	ds_read_b128 v[138:141], v119 offset:16384
	ds_read_b128 v[142:145], v119 offset:24576
	s_mov_b64 s[24:25], s[16:17]
	s_waitcnt lgkmcnt(3)
	global_store_dwordx4 v122, v[130:133], s[24:25]
	s_add_u32 s24, s24, 0x80000
	s_addc_u32 s25, s25, 0
	s_waitcnt lgkmcnt(2)
	global_store_dwordx4 v122, v[134:137], s[24:25]
	s_add_u32 s24, s24, 0x80000
	s_addc_u32 s25, s25, 0
	s_waitcnt lgkmcnt(1)
	global_store_dwordx4 v122, v[138:141], s[24:25]
	s_add_u32 s24, s24, 0x80000
	s_addc_u32 s25, s25, 0
	s_waitcnt lgkmcnt(0)
	global_store_dwordx4 v122, v[142:145], s[24:25]
	s_add_u32 s16, s16, 0x200000
	s_addc_u32 s17, s17, 0
	s_add_i32 s28, s28, 1
	s_cmp_lt_u32 s28, 8
	s_cbranch_scc1 .Llr_sc
	s_waitcnt lgkmcnt(0)
	s_branch .LBB0_1026
.Llr_orig:
	s_load_dwordx2 s[8:9], s[0:1], 0xf0
	v_and_b32_e32 v80, 31, v4
	v_lshlrev_b32_e32 v5, 2, v80
	v_lshlrev_b32_e32 v7, 2, v4
	v_ashrrev_i32_e32 v0, 5, v4
	s_waitcnt lgkmcnt(0)
	s_add_u32 s14, s8, 0x13f00000
	s_addc_u32 s15, s9, 0
	s_add_u32 s16, s8, 0x7f00000
	s_addc_u32 s17, s9, 0
	s_add_i32 s3, 0, 0x11000
	s_add_u32 s24, s8, 0xbf01000
	v_cmp_gt_i32_e64 s[6:7], 32, v4
	v_add_u32_e32 v81, s3, v7
	v_and_b32_e32 v2, 0xffffffe0, v4
	s_addc_u32 s25, s9, 0
	s_add_i32 s8, 0, 0x10000
	s_add_i32 s12, 0, 0x10800
	v_add_u32_e32 v85, s3, v5
	v_lshlrev_b32_e32 v4, 7, v4
	s_movk_i32 s3, 0xf000
	v_add_u32_e32 v6, 0, v5
	v_add_u32_e32 v83, s8, v7
	v_add_u32_e32 v84, s12, v7
	v_lshlrev_b32_e32 v7, 7, v2
	v_or_b32_e32 v8, 0xf80, v4
	v_and_or_b32 v4, v4, s3, v5
	s_mov_b32 s13, 0
	v_ashrrev_i32_e32 v1, 31, v0
	v_lshl_add_u32 v82, v2, 2, v6
	v_ashrrev_i32_e32 v3, 31, v2
	v_cmp_lt_i32_e64 s[8:9], 0, v0
	v_cmp_eq_u32_e64 s[10:11], 15, v0
	v_add_u32_e32 v86, 0, v4
	v_add_u32_e32 v87, s12, v5
	v_mov_b32_e32 v5, 0
	v_add_u32_e32 v88, v6, v7
	v_add_u32_e32 v89, v6, v8
	s_mov_b32 s3, s2
	s_branch .LBB0_1012
